# K-loop LDS-DMA loads in SADDR form (scalar base + 32-bit per-lane offset), no per-load 64-bit VALU address adds in the load segments
# speedup vs baseline: 1.0086x; 1.0086x over previous
.LBB0_333:
	s_add_i32 s51, s50, 2
	s_add_u32 s52, s42, 0x80
	s_addc_u32 s53, s43, 0
	s_add_i32 s54, 0, 0x10000
	s_cmp_eq_u32 s87, s50
	s_cselect_b32 s79, s1, s53
	s_cselect_b32 s78, s0, s52
	v_add_u32_e32 v144, s54, v147
	s_cselect_b32 s53, s75, s49
	s_cselect_b32 s52, s74, s48
	s_add_i32 s50, 0, 0x14000
	s_waitcnt lgkmcnt(0)
	ds_read_b128 v[140:143], v144
	ds_read_b128 v[162:165], v144 offset:1024
	ds_read_b128 v[166:169], v144 offset:2048
	ds_read_b128 v[170:173], v144 offset:3072
	v_add_u32_e32 v144, s50, v147
	ds_read_b128 v[174:177], v144
	ds_read_b128 v[178:181], v144 offset:1024
	ds_read_b128 v[182:185], v144 offset:2048
	ds_read_b128 v[186:189], v144 offset:3072
	s_add_i32 m0, s9, 0xc000
	ds_read_b128 v[190:193], v149
	ds_read_b128 v[194:197], v149 offset:1024
	ds_read_b128 v[198:201], v149 offset:2048
	ds_read_b128 v[202:205], v149 offset:3072
	ds_read_b128 v[206:209], v149 offset:4096
	ds_read_b128 v[210:213], v149 offset:5120
	ds_read_b128 v[214:217], v149 offset:6144
	ds_read_b128 v[218:221], v149 offset:7168
	global_load_lds_dwordx4 v136, s[42:43]
	s_add_i32 m0, s9, 0xe000
	s_nop 0
	global_load_lds_dwordx4 v138, s[42:43]
	s_waitcnt vmcnt(8)
	s_waitcnt lgkmcnt(0)
	s_barrier
	s_setprio 1
	s_waitcnt lgkmcnt(0)
	v_mfma_f32_16x16x32_bf16 v[126:129], v[140:143], v[190:193], v[126:129]
	v_mfma_f32_16x16x32_bf16 v[122:125], v[166:169], v[190:193], v[122:125]
	v_mfma_f32_16x16x32_bf16 v[110:113], v[140:143], v[198:201], v[110:113]
	v_mfma_f32_16x16x32_bf16 v[106:109], v[166:169], v[198:201], v[106:109]
	v_mfma_f32_16x16x32_bf16 v[92:95], v[140:143], v[206:209], v[92:95]
	v_mfma_f32_16x16x32_bf16 v[88:91], v[166:169], v[206:209], v[88:91]
	v_mfma_f32_16x16x32_bf16 v[76:79], v[140:143], v[214:217], v[76:79]
	v_mfma_f32_16x16x32_bf16 v[72:75], v[166:169], v[214:217], v[72:75]
	v_mfma_f32_16x16x32_bf16 v[126:129], v[162:165], v[194:197], v[126:129]
	v_mfma_f32_16x16x32_bf16 v[122:125], v[170:173], v[194:197], v[122:125]
	v_mfma_f32_16x16x32_bf16 v[110:113], v[162:165], v[202:205], v[110:113]
	v_mfma_f32_16x16x32_bf16 v[106:109], v[170:173], v[202:205], v[106:109]
	v_mfma_f32_16x16x32_bf16 v[92:95], v[162:165], v[210:213], v[92:95]
	v_mfma_f32_16x16x32_bf16 v[88:91], v[170:173], v[210:213], v[88:91]
	v_mfma_f32_16x16x32_bf16 v[76:79], v[162:165], v[218:221], v[76:79]
	v_mfma_f32_16x16x32_bf16 v[72:75], v[170:173], v[218:221], v[72:75]
	s_setprio 0
	s_setprio 1
	v_mfma_f32_16x16x32_bf16 v[118:121], v[174:177], v[190:193], v[118:121]
	v_mfma_f32_16x16x32_bf16 v[114:117], v[182:185], v[190:193], v[114:117]
	v_mfma_f32_16x16x32_bf16 v[102:105], v[174:177], v[198:201], v[102:105]
	v_mfma_f32_16x16x32_bf16 v[98:101], v[182:185], v[198:201], v[98:101]
	v_mfma_f32_16x16x32_bf16 v[84:87], v[174:177], v[206:209], v[84:87]
	v_mfma_f32_16x16x32_bf16 v[80:83], v[182:185], v[206:209], v[80:83]
	v_mfma_f32_16x16x32_bf16 v[68:71], v[174:177], v[214:217], v[68:71]
	v_mfma_f32_16x16x32_bf16 v[64:67], v[182:185], v[214:217], v[64:67]
	v_mfma_f32_16x16x32_bf16 v[118:121], v[178:181], v[194:197], v[118:121]
	v_mfma_f32_16x16x32_bf16 v[114:117], v[186:189], v[194:197], v[114:117]
	v_mfma_f32_16x16x32_bf16 v[102:105], v[178:181], v[202:205], v[102:105]
	v_mfma_f32_16x16x32_bf16 v[98:101], v[186:189], v[202:205], v[98:101]
	v_mfma_f32_16x16x32_bf16 v[84:87], v[178:181], v[210:213], v[84:87]
	v_mfma_f32_16x16x32_bf16 v[80:83], v[186:189], v[210:213], v[80:83]
	v_mfma_f32_16x16x32_bf16 v[68:71], v[178:181], v[218:221], v[68:71]
	v_mfma_f32_16x16x32_bf16 v[64:67], v[186:189], v[218:221], v[64:67]
	s_setprio 0
	s_barrier
	s_add_i32 s54, s54, s8
	s_add_u32 s100, s52, s12
	s_addc_u32 s101, s53, s13
	s_mov_b32 m0, s54
	ds_read_b128 v[190:193], v149 offset:16384
	ds_read_b128 v[194:197], v149 offset:17408
	ds_read_b128 v[198:201], v149 offset:18432
	ds_read_b128 v[202:205], v149 offset:19456
	ds_read_b128 v[206:209], v149 offset:20480
	ds_read_b128 v[210:213], v149 offset:21504
	ds_read_b128 v[214:217], v149 offset:22528
	ds_read_b128 v[218:221], v149 offset:23552
	global_load_lds_dwordx4 v96, s[52:53]
	s_add_i32 m0, s54, 0x2000
	s_add_i32 s50, s50, s8
	global_load_lds_dwordx4 v134, s[52:53]
	s_add_u32 s52, s52, s34
	s_addc_u32 s53, s53, s35
	s_mov_b32 m0, s50
	s_nop 0
	global_load_lds_dwordx4 v96, s[52:53]
	s_add_i32 m0, s50, 0x2000
	s_nop 0
	global_load_lds_dwordx4 v134, s[52:53]
	s_mov_b32 m0, s9
	s_nop 0
	global_load_lds_dwordx4 v130, s[78:79]
	s_mov_b32 m0, s98
	s_nop 0
	global_load_lds_dwordx4 v132, s[78:79]
	s_waitcnt vmcnt(8)
	s_waitcnt lgkmcnt(0)
	s_barrier
	s_setprio 1
	s_waitcnt lgkmcnt(0)
	v_mfma_f32_16x16x32_bf16 v[60:63], v[140:143], v[190:193], v[60:63]
	v_mfma_f32_16x16x32_bf16 v[56:59], v[166:169], v[190:193], v[56:59]
	v_mfma_f32_16x16x32_bf16 v[44:47], v[140:143], v[198:201], v[44:47]
	v_mfma_f32_16x16x32_bf16 v[40:43], v[166:169], v[198:201], v[40:43]
	v_mfma_f32_16x16x32_bf16 v[28:31], v[140:143], v[206:209], v[28:31]
	v_mfma_f32_16x16x32_bf16 v[24:27], v[166:169], v[206:209], v[24:27]
	v_mfma_f32_16x16x32_bf16 v[12:15], v[140:143], v[214:217], v[12:15]
	v_mfma_f32_16x16x32_bf16 v[8:11], v[166:169], v[214:217], v[8:11]
	v_mfma_f32_16x16x32_bf16 v[60:63], v[162:165], v[194:197], v[60:63]
	v_mfma_f32_16x16x32_bf16 v[56:59], v[170:173], v[194:197], v[56:59]
	v_mfma_f32_16x16x32_bf16 v[44:47], v[162:165], v[202:205], v[44:47]
	v_mfma_f32_16x16x32_bf16 v[40:43], v[170:173], v[202:205], v[40:43]
	v_mfma_f32_16x16x32_bf16 v[28:31], v[162:165], v[210:213], v[28:31]
	v_mfma_f32_16x16x32_bf16 v[24:27], v[170:173], v[210:213], v[24:27]
	v_mfma_f32_16x16x32_bf16 v[12:15], v[162:165], v[218:221], v[12:15]
	v_mfma_f32_16x16x32_bf16 v[8:11], v[170:173], v[218:221], v[8:11]
	s_setprio 0
	s_setprio 1
	v_mfma_f32_16x16x32_bf16 v[52:55], v[174:177], v[190:193], v[52:55]
	v_mfma_f32_16x16x32_bf16 v[48:51], v[182:185], v[190:193], v[48:51]
	v_mfma_f32_16x16x32_bf16 v[36:39], v[174:177], v[198:201], v[36:39]
	v_mfma_f32_16x16x32_bf16 v[32:35], v[182:185], v[198:201], v[32:35]
	v_mfma_f32_16x16x32_bf16 v[20:23], v[174:177], v[206:209], v[20:23]
	v_mfma_f32_16x16x32_bf16 v[16:19], v[182:185], v[206:209], v[16:19]
	v_mfma_f32_16x16x32_bf16 v[4:7], v[174:177], v[214:217], v[4:7]
	v_mfma_f32_16x16x32_bf16 v[0:3], v[182:185], v[214:217], v[0:3]
	v_mfma_f32_16x16x32_bf16 v[52:55], v[178:181], v[194:197], v[52:55]
	v_mfma_f32_16x16x32_bf16 v[48:51], v[186:189], v[194:197], v[48:51]
	v_mfma_f32_16x16x32_bf16 v[36:39], v[178:181], v[202:205], v[36:39]
	v_mfma_f32_16x16x32_bf16 v[32:35], v[186:189], v[202:205], v[32:35]
	v_mfma_f32_16x16x32_bf16 v[20:23], v[178:181], v[210:213], v[20:23]
	v_mfma_f32_16x16x32_bf16 v[16:19], v[186:189], v[210:213], v[16:19]
	v_mfma_f32_16x16x32_bf16 v[4:7], v[178:181], v[218:221], v[4:7]
	v_mfma_f32_16x16x32_bf16 v[0:3], v[186:189], v[218:221], v[0:3]
	s_setprio 0
	s_barrier
	s_add_i32 s50, 0, 0x18000
	v_add_u32_e32 v161, s50, v147
	s_add_i32 s54, 0, 0x1c000
	ds_read_b128 v[140:143], v161
	ds_read_b128 v[162:165], v161 offset:1024
	ds_read_b128 v[166:169], v161 offset:2048
	ds_read_b128 v[170:173], v161 offset:3072
	v_add_u32_e32 v161, s54, v147
	ds_read_b128 v[174:177], v161
	ds_read_b128 v[178:181], v161 offset:1024
	ds_read_b128 v[182:185], v161 offset:2048
	ds_read_b128 v[186:189], v161 offset:3072
	s_add_u32 s52, s78, s34
	s_addc_u32 s53, s79, s35
	s_mov_b32 m0, s99
	ds_read_b128 v[190:193], v149 offset:32768
	ds_read_b128 v[194:197], v149 offset:33792
	ds_read_b128 v[198:201], v149 offset:34816
	ds_read_b128 v[202:205], v149 offset:35840
	ds_read_b128 v[206:209], v149 offset:36864
	ds_read_b128 v[210:213], v149 offset:37888
	ds_read_b128 v[214:217], v149 offset:38912
	ds_read_b128 v[218:221], v149 offset:39936
	global_load_lds_dwordx4 v130, s[52:53]
	s_mov_b32 m0, s76
	s_nop 0
	global_load_lds_dwordx4 v132, s[52:53]
	s_waitcnt vmcnt(8)
	s_waitcnt lgkmcnt(0)
	s_barrier
	s_setprio 1
	s_waitcnt lgkmcnt(0)
	v_mfma_f32_16x16x32_bf16 v[126:129], v[140:143], v[190:193], v[126:129]
	v_mfma_f32_16x16x32_bf16 v[122:125], v[166:169], v[190:193], v[122:125]
	v_mfma_f32_16x16x32_bf16 v[110:113], v[140:143], v[198:201], v[110:113]
	v_mfma_f32_16x16x32_bf16 v[106:109], v[166:169], v[198:201], v[106:109]
	v_mfma_f32_16x16x32_bf16 v[92:95], v[140:143], v[206:209], v[92:95]
	v_mfma_f32_16x16x32_bf16 v[88:91], v[166:169], v[206:209], v[88:91]
	v_mfma_f32_16x16x32_bf16 v[76:79], v[140:143], v[214:217], v[76:79]
	v_mfma_f32_16x16x32_bf16 v[72:75], v[166:169], v[214:217], v[72:75]
	v_mfma_f32_16x16x32_bf16 v[126:129], v[162:165], v[194:197], v[126:129]
	v_mfma_f32_16x16x32_bf16 v[122:125], v[170:173], v[194:197], v[122:125]
	v_mfma_f32_16x16x32_bf16 v[110:113], v[162:165], v[202:205], v[110:113]
	v_mfma_f32_16x16x32_bf16 v[106:109], v[170:173], v[202:205], v[106:109]
	v_mfma_f32_16x16x32_bf16 v[92:95], v[162:165], v[210:213], v[92:95]
	v_mfma_f32_16x16x32_bf16 v[88:91], v[170:173], v[210:213], v[88:91]
	v_mfma_f32_16x16x32_bf16 v[76:79], v[162:165], v[218:221], v[76:79]
	v_mfma_f32_16x16x32_bf16 v[72:75], v[170:173], v[218:221], v[72:75]
	s_setprio 0
	s_setprio 1
	v_mfma_f32_16x16x32_bf16 v[118:121], v[174:177], v[190:193], v[118:121]
	v_mfma_f32_16x16x32_bf16 v[114:117], v[182:185], v[190:193], v[114:117]
	v_mfma_f32_16x16x32_bf16 v[102:105], v[174:177], v[198:201], v[102:105]
	v_mfma_f32_16x16x32_bf16 v[98:101], v[182:185], v[198:201], v[98:101]
	v_mfma_f32_16x16x32_bf16 v[84:87], v[174:177], v[206:209], v[84:87]
	v_mfma_f32_16x16x32_bf16 v[80:83], v[182:185], v[206:209], v[80:83]
	v_mfma_f32_16x16x32_bf16 v[68:71], v[174:177], v[214:217], v[68:71]
	v_mfma_f32_16x16x32_bf16 v[64:67], v[182:185], v[214:217], v[64:67]
	v_mfma_f32_16x16x32_bf16 v[118:121], v[178:181], v[194:197], v[118:121]
	v_mfma_f32_16x16x32_bf16 v[114:117], v[186:189], v[194:197], v[114:117]
	v_mfma_f32_16x16x32_bf16 v[102:105], v[178:181], v[202:205], v[102:105]
	v_mfma_f32_16x16x32_bf16 v[98:101], v[186:189], v[202:205], v[98:101]
	v_mfma_f32_16x16x32_bf16 v[84:87], v[178:181], v[210:213], v[84:87]
	v_mfma_f32_16x16x32_bf16 v[80:83], v[186:189], v[210:213], v[80:83]
	v_mfma_f32_16x16x32_bf16 v[68:71], v[178:181], v[218:221], v[68:71]
	v_mfma_f32_16x16x32_bf16 v[64:67], v[186:189], v[218:221], v[64:67]
	s_setprio 0
	s_barrier
	s_add_i32 s50, s50, s8
	s_mov_b32 m0, s50
	ds_read_b128 v[190:193], v149 offset:49152
	ds_read_b128 v[194:197], v149 offset:50176
	ds_read_b128 v[198:201], v149 offset:51200
	ds_read_b128 v[202:205], v149 offset:52224
	ds_read_b128 v[206:209], v149 offset:53248
	ds_read_b128 v[210:213], v149 offset:54272
	ds_read_b128 v[214:217], v149 offset:55296
	ds_read_b128 v[218:221], v149 offset:56320
	global_load_lds_dwordx4 v96, s[100:101]
	s_add_i32 m0, s50, 0x2000
	s_add_i32 s50, s54, s8
	global_load_lds_dwordx4 v134, s[100:101]
	s_mov_b32 m0, s50
	s_nop 0
	s_add_u32 s100, s100, s34
	s_addc_u32 s101, s101, s35
	global_load_lds_dwordx4 v96, s[100:101]
	s_add_i32 m0, s50, 0x2000
	s_nop 0
	global_load_lds_dwordx4 v134, s[100:101]
	s_mov_b32 m0, s77
	s_nop 0
	s_add_u32 s100, s78, s12
	s_addc_u32 s101, s79, s13
	global_load_lds_dwordx4 v130, s[100:101]
	s_mov_b32 m0, s86
	s_nop 0
	global_load_lds_dwordx4 v132, s[100:101]
	s_waitcnt vmcnt(8)
	s_waitcnt lgkmcnt(0)
	s_barrier
	s_setprio 1
	s_waitcnt lgkmcnt(0)
	v_mfma_f32_16x16x32_bf16 v[60:63], v[140:143], v[190:193], v[60:63]
	v_mfma_f32_16x16x32_bf16 v[56:59], v[166:169], v[190:193], v[56:59]
	v_mfma_f32_16x16x32_bf16 v[44:47], v[140:143], v[198:201], v[44:47]
	v_mfma_f32_16x16x32_bf16 v[40:43], v[166:169], v[198:201], v[40:43]
	v_mfma_f32_16x16x32_bf16 v[28:31], v[140:143], v[206:209], v[28:31]
	v_mfma_f32_16x16x32_bf16 v[24:27], v[166:169], v[206:209], v[24:27]
	v_mfma_f32_16x16x32_bf16 v[12:15], v[140:143], v[214:217], v[12:15]
	v_mfma_f32_16x16x32_bf16 v[8:11], v[166:169], v[214:217], v[8:11]
	v_mfma_f32_16x16x32_bf16 v[60:63], v[162:165], v[194:197], v[60:63]
	v_mfma_f32_16x16x32_bf16 v[56:59], v[170:173], v[194:197], v[56:59]
	v_mfma_f32_16x16x32_bf16 v[44:47], v[162:165], v[202:205], v[44:47]
	v_mfma_f32_16x16x32_bf16 v[40:43], v[170:173], v[202:205], v[40:43]
	v_mfma_f32_16x16x32_bf16 v[28:31], v[162:165], v[210:213], v[28:31]
	v_mfma_f32_16x16x32_bf16 v[24:27], v[170:173], v[210:213], v[24:27]
	v_mfma_f32_16x16x32_bf16 v[12:15], v[162:165], v[218:221], v[12:15]
	v_mfma_f32_16x16x32_bf16 v[8:11], v[170:173], v[218:221], v[8:11]
	s_setprio 0
	s_setprio 1
	v_mfma_f32_16x16x32_bf16 v[52:55], v[174:177], v[190:193], v[52:55]
	v_mfma_f32_16x16x32_bf16 v[48:51], v[182:185], v[190:193], v[48:51]
	v_mfma_f32_16x16x32_bf16 v[36:39], v[174:177], v[198:201], v[36:39]
	v_mfma_f32_16x16x32_bf16 v[32:35], v[182:185], v[198:201], v[32:35]
	v_mfma_f32_16x16x32_bf16 v[20:23], v[174:177], v[206:209], v[20:23]
	v_mfma_f32_16x16x32_bf16 v[16:19], v[182:185], v[206:209], v[16:19]
	v_mfma_f32_16x16x32_bf16 v[4:7], v[174:177], v[214:217], v[4:7]
	v_mfma_f32_16x16x32_bf16 v[0:3], v[182:185], v[214:217], v[0:3]
	v_mfma_f32_16x16x32_bf16 v[52:55], v[178:181], v[194:197], v[52:55]
	v_mfma_f32_16x16x32_bf16 v[48:51], v[186:189], v[194:197], v[48:51]
	v_mfma_f32_16x16x32_bf16 v[36:39], v[178:181], v[202:205], v[36:39]
	v_mfma_f32_16x16x32_bf16 v[32:35], v[186:189], v[202:205], v[32:35]
	v_mfma_f32_16x16x32_bf16 v[20:23], v[178:181], v[210:213], v[20:23]
	v_mfma_f32_16x16x32_bf16 v[16:19], v[186:189], v[210:213], v[16:19]
	v_mfma_f32_16x16x32_bf16 v[4:7], v[178:181], v[218:221], v[4:7]
	v_mfma_f32_16x16x32_bf16 v[0:3], v[186:189], v[218:221], v[0:3]
	s_setprio 0
	s_barrier
	s_add_u32 s42, s42, 0x100
	s_addc_u32 s43, s43, 0
	s_add_u32 s48, s48, 0x100
	s_addc_u32 s49, s49, 0
	s_cmp_ge_u32 s51, s64
	s_mov_b32 s50, s51
	s_cbranch_scc0 .LBB0_333
.Lk_done:
	s_add_u32 s52, s0, 0x80
	s_addc_u32 s53, s1, 0
	s_add_i32 m0, s9, 0xc000
	s_nop 0
	global_load_lds_dwordx4 v136, s[52:53]
	s_add_i32 m0, s9, 0xe000
	s_nop 0
	global_load_lds_dwordx4 v138, s[52:53]
	v_readlane_b32 s42, v233, 50
	v_readlane_b32 s43, v233, 51
	s_and_b64 vcc, exec, s[42:43]
	s_cbranch_vccz .LBB0_336
	s_barrier

.Lk_peel:
	s_add_i32 s51, s50, 2
	s_add_u32 s52, s42, 0x80
	s_addc_u32 s53, s43, 0
	s_add_i32 s54, 0, 0x10000
	s_cmp_eq_u32 s87, s50
	s_cselect_b32 s79, s1, s53
	s_cselect_b32 s78, s0, s52
	v_add_u32_e32 v144, s54, v147
	s_cselect_b32 s53, s75, s49
	s_cselect_b32 s52, s74, s48
	s_add_i32 s50, 0, 0x14000
	s_waitcnt lgkmcnt(0)
	ds_read_b128 v[140:143], v144
	ds_read_b128 v[162:165], v144 offset:1024
	ds_read_b128 v[166:169], v144 offset:2048
	ds_read_b128 v[170:173], v144 offset:3072
	v_add_u32_e32 v144, s50, v147
	ds_read_b128 v[174:177], v144
	ds_read_b128 v[178:181], v144 offset:1024
	ds_read_b128 v[182:185], v144 offset:2048
	ds_read_b128 v[186:189], v144 offset:3072
	ds_read_b128 v[190:193], v149
	ds_read_b128 v[194:197], v149 offset:1024
	ds_read_b128 v[198:201], v149 offset:2048
	ds_read_b128 v[202:205], v149 offset:3072
	ds_read_b128 v[206:209], v149 offset:4096
	ds_read_b128 v[210:213], v149 offset:5120
	ds_read_b128 v[214:217], v149 offset:6144
	ds_read_b128 v[218:221], v149 offset:7168
	s_waitcnt vmcnt(16)
	s_waitcnt lgkmcnt(0)
	s_barrier
	s_setprio 1
	s_waitcnt lgkmcnt(0)
	v_mfma_f32_16x16x32_bf16 v[126:129], v[140:143], v[190:193], 0
	v_mfma_f32_16x16x32_bf16 v[122:125], v[166:169], v[190:193], 0
	v_mfma_f32_16x16x32_bf16 v[110:113], v[140:143], v[198:201], 0
	v_mfma_f32_16x16x32_bf16 v[106:109], v[166:169], v[198:201], 0
	v_mfma_f32_16x16x32_bf16 v[92:95], v[140:143], v[206:209], 0
	v_mfma_f32_16x16x32_bf16 v[88:91], v[166:169], v[206:209], 0
	v_mfma_f32_16x16x32_bf16 v[76:79], v[140:143], v[214:217], 0
	v_mfma_f32_16x16x32_bf16 v[72:75], v[166:169], v[214:217], 0
	v_mfma_f32_16x16x32_bf16 v[126:129], v[162:165], v[194:197], v[126:129]
	v_mfma_f32_16x16x32_bf16 v[122:125], v[170:173], v[194:197], v[122:125]
	v_mfma_f32_16x16x32_bf16 v[110:113], v[162:165], v[202:205], v[110:113]
	v_mfma_f32_16x16x32_bf16 v[106:109], v[170:173], v[202:205], v[106:109]
	v_mfma_f32_16x16x32_bf16 v[92:95], v[162:165], v[210:213], v[92:95]
	v_mfma_f32_16x16x32_bf16 v[88:91], v[170:173], v[210:213], v[88:91]
	v_mfma_f32_16x16x32_bf16 v[76:79], v[162:165], v[218:221], v[76:79]
	v_mfma_f32_16x16x32_bf16 v[72:75], v[170:173], v[218:221], v[72:75]
	s_setprio 0
	s_setprio 1
	v_mfma_f32_16x16x32_bf16 v[118:121], v[174:177], v[190:193], 0
	v_mfma_f32_16x16x32_bf16 v[114:117], v[182:185], v[190:193], 0
	v_mfma_f32_16x16x32_bf16 v[102:105], v[174:177], v[198:201], 0
	v_mfma_f32_16x16x32_bf16 v[98:101], v[182:185], v[198:201], 0
	v_mfma_f32_16x16x32_bf16 v[84:87], v[174:177], v[206:209], 0
	v_mfma_f32_16x16x32_bf16 v[80:83], v[182:185], v[206:209], 0
	v_mfma_f32_16x16x32_bf16 v[68:71], v[174:177], v[214:217], 0
	v_mfma_f32_16x16x32_bf16 v[64:67], v[182:185], v[214:217], 0
	v_mfma_f32_16x16x32_bf16 v[118:121], v[178:181], v[194:197], v[118:121]
	v_mfma_f32_16x16x32_bf16 v[114:117], v[186:189], v[194:197], v[114:117]
	v_mfma_f32_16x16x32_bf16 v[102:105], v[178:181], v[202:205], v[102:105]
	v_mfma_f32_16x16x32_bf16 v[98:101], v[186:189], v[202:205], v[98:101]
	v_mfma_f32_16x16x32_bf16 v[84:87], v[178:181], v[210:213], v[84:87]
	v_mfma_f32_16x16x32_bf16 v[80:83], v[186:189], v[210:213], v[80:83]
	v_mfma_f32_16x16x32_bf16 v[68:71], v[178:181], v[218:221], v[68:71]
	v_mfma_f32_16x16x32_bf16 v[64:67], v[186:189], v[218:221], v[64:67]
	s_setprio 0
	s_barrier
	s_add_i32 s54, s54, s8
	s_add_u32 s100, s52, s12
	s_addc_u32 s101, s53, s13
	s_mov_b32 m0, s54
	ds_read_b128 v[190:193], v149 offset:16384
	ds_read_b128 v[194:197], v149 offset:17408
	ds_read_b128 v[198:201], v149 offset:18432
	ds_read_b128 v[202:205], v149 offset:19456
	ds_read_b128 v[206:209], v149 offset:20480
	ds_read_b128 v[210:213], v149 offset:21504
	ds_read_b128 v[214:217], v149 offset:22528
	ds_read_b128 v[218:221], v149 offset:23552
	global_load_lds_dwordx4 v96, s[52:53]
	s_add_i32 m0, s54, 0x2000
	s_add_i32 s50, s50, s8
	global_load_lds_dwordx4 v134, s[52:53]
	s_add_u32 s52, s52, s34
	s_addc_u32 s53, s53, s35
	s_mov_b32 m0, s50
	s_nop 0
	global_load_lds_dwordx4 v96, s[52:53]
	s_add_i32 m0, s50, 0x2000
	s_nop 0
	global_load_lds_dwordx4 v134, s[52:53]
	s_mov_b32 m0, s9
	s_nop 0
	global_load_lds_dwordx4 v130, s[78:79]
	s_mov_b32 m0, s98
	s_nop 0
	global_load_lds_dwordx4 v132, s[78:79]
	s_waitcnt vmcnt(16)
	s_waitcnt lgkmcnt(0)
	s_barrier
	s_setprio 1
	s_waitcnt lgkmcnt(0)
	v_mfma_f32_16x16x32_bf16 v[60:63], v[140:143], v[190:193], 0
	v_mfma_f32_16x16x32_bf16 v[56:59], v[166:169], v[190:193], 0
	v_mfma_f32_16x16x32_bf16 v[44:47], v[140:143], v[198:201], 0
	v_mfma_f32_16x16x32_bf16 v[40:43], v[166:169], v[198:201], 0
	v_mfma_f32_16x16x32_bf16 v[28:31], v[140:143], v[206:209], 0
	v_mfma_f32_16x16x32_bf16 v[24:27], v[166:169], v[206:209], 0
	v_mfma_f32_16x16x32_bf16 v[12:15], v[140:143], v[214:217], 0
	v_mfma_f32_16x16x32_bf16 v[8:11], v[166:169], v[214:217], 0
	v_mfma_f32_16x16x32_bf16 v[60:63], v[162:165], v[194:197], v[60:63]
	v_mfma_f32_16x16x32_bf16 v[56:59], v[170:173], v[194:197], v[56:59]
	v_mfma_f32_16x16x32_bf16 v[44:47], v[162:165], v[202:205], v[44:47]
	v_mfma_f32_16x16x32_bf16 v[40:43], v[170:173], v[202:205], v[40:43]
	v_mfma_f32_16x16x32_bf16 v[28:31], v[162:165], v[210:213], v[28:31]
	v_mfma_f32_16x16x32_bf16 v[24:27], v[170:173], v[210:213], v[24:27]
	v_mfma_f32_16x16x32_bf16 v[12:15], v[162:165], v[218:221], v[12:15]
	v_mfma_f32_16x16x32_bf16 v[8:11], v[170:173], v[218:221], v[8:11]
	s_setprio 0
	s_setprio 1
	v_mfma_f32_16x16x32_bf16 v[52:55], v[174:177], v[190:193], 0
	v_mfma_f32_16x16x32_bf16 v[48:51], v[182:185], v[190:193], 0
	v_mfma_f32_16x16x32_bf16 v[36:39], v[174:177], v[198:201], 0
	v_mfma_f32_16x16x32_bf16 v[32:35], v[182:185], v[198:201], 0
	v_mfma_f32_16x16x32_bf16 v[20:23], v[174:177], v[206:209], 0
	v_mfma_f32_16x16x32_bf16 v[16:19], v[182:185], v[206:209], 0
	v_mfma_f32_16x16x32_bf16 v[4:7], v[174:177], v[214:217], 0
	v_mfma_f32_16x16x32_bf16 v[0:3], v[182:185], v[214:217], 0
	v_mfma_f32_16x16x32_bf16 v[52:55], v[178:181], v[194:197], v[52:55]
	v_mfma_f32_16x16x32_bf16 v[48:51], v[186:189], v[194:197], v[48:51]
	v_mfma_f32_16x16x32_bf16 v[36:39], v[178:181], v[202:205], v[36:39]
	v_mfma_f32_16x16x32_bf16 v[32:35], v[186:189], v[202:205], v[32:35]
	v_mfma_f32_16x16x32_bf16 v[20:23], v[178:181], v[210:213], v[20:23]
	v_mfma_f32_16x16x32_bf16 v[16:19], v[186:189], v[210:213], v[16:19]
	v_mfma_f32_16x16x32_bf16 v[4:7], v[178:181], v[218:221], v[4:7]
	v_mfma_f32_16x16x32_bf16 v[0:3], v[186:189], v[218:221], v[0:3]
	s_setprio 0
	s_barrier
	s_add_i32 s50, 0, 0x18000
	v_add_u32_e32 v161, s50, v147
	s_add_i32 s54, 0, 0x1c000
	ds_read_b128 v[140:143], v161
	ds_read_b128 v[162:165], v161 offset:1024
	ds_read_b128 v[166:169], v161 offset:2048
	ds_read_b128 v[170:173], v161 offset:3072
	v_add_u32_e32 v161, s54, v147
	ds_read_b128 v[174:177], v161
	ds_read_b128 v[178:181], v161 offset:1024
	ds_read_b128 v[182:185], v161 offset:2048
	ds_read_b128 v[186:189], v161 offset:3072
	s_add_u32 s52, s78, s34
	s_addc_u32 s53, s79, s35
	s_mov_b32 m0, s99
	ds_read_b128 v[190:193], v149 offset:32768
	ds_read_b128 v[194:197], v149 offset:33792
	ds_read_b128 v[198:201], v149 offset:34816
	ds_read_b128 v[202:205], v149 offset:35840
	ds_read_b128 v[206:209], v149 offset:36864
	ds_read_b128 v[210:213], v149 offset:37888
	ds_read_b128 v[214:217], v149 offset:38912
	ds_read_b128 v[218:221], v149 offset:39936
	global_load_lds_dwordx4 v130, s[52:53]
	s_mov_b32 m0, s76
	s_nop 0
	global_load_lds_dwordx4 v132, s[52:53]
	s_waitcnt vmcnt(16)
	s_waitcnt lgkmcnt(0)
	s_barrier
	s_setprio 1
	s_waitcnt lgkmcnt(0)
	v_mfma_f32_16x16x32_bf16 v[126:129], v[140:143], v[190:193], v[126:129]
	v_mfma_f32_16x16x32_bf16 v[122:125], v[166:169], v[190:193], v[122:125]
	v_mfma_f32_16x16x32_bf16 v[110:113], v[140:143], v[198:201], v[110:113]
	v_mfma_f32_16x16x32_bf16 v[106:109], v[166:169], v[198:201], v[106:109]
	v_mfma_f32_16x16x32_bf16 v[92:95], v[140:143], v[206:209], v[92:95]
	v_mfma_f32_16x16x32_bf16 v[88:91], v[166:169], v[206:209], v[88:91]
	v_mfma_f32_16x16x32_bf16 v[76:79], v[140:143], v[214:217], v[76:79]
	v_mfma_f32_16x16x32_bf16 v[72:75], v[166:169], v[214:217], v[72:75]
	v_mfma_f32_16x16x32_bf16 v[126:129], v[162:165], v[194:197], v[126:129]
	v_mfma_f32_16x16x32_bf16 v[122:125], v[170:173], v[194:197], v[122:125]
	v_mfma_f32_16x16x32_bf16 v[110:113], v[162:165], v[202:205], v[110:113]
	v_mfma_f32_16x16x32_bf16 v[106:109], v[170:173], v[202:205], v[106:109]
	v_mfma_f32_16x16x32_bf16 v[92:95], v[162:165], v[210:213], v[92:95]
	v_mfma_f32_16x16x32_bf16 v[88:91], v[170:173], v[210:213], v[88:91]
	v_mfma_f32_16x16x32_bf16 v[76:79], v[162:165], v[218:221], v[76:79]
	v_mfma_f32_16x16x32_bf16 v[72:75], v[170:173], v[218:221], v[72:75]
	s_setprio 0
	s_setprio 1
	v_mfma_f32_16x16x32_bf16 v[118:121], v[174:177], v[190:193], v[118:121]
	v_mfma_f32_16x16x32_bf16 v[114:117], v[182:185], v[190:193], v[114:117]
	v_mfma_f32_16x16x32_bf16 v[102:105], v[174:177], v[198:201], v[102:105]
	v_mfma_f32_16x16x32_bf16 v[98:101], v[182:185], v[198:201], v[98:101]
	v_mfma_f32_16x16x32_bf16 v[84:87], v[174:177], v[206:209], v[84:87]
	v_mfma_f32_16x16x32_bf16 v[80:83], v[182:185], v[206:209], v[80:83]
	v_mfma_f32_16x16x32_bf16 v[68:71], v[174:177], v[214:217], v[68:71]
	v_mfma_f32_16x16x32_bf16 v[64:67], v[182:185], v[214:217], v[64:67]
	v_mfma_f32_16x16x32_bf16 v[118:121], v[178:181], v[194:197], v[118:121]
	v_mfma_f32_16x16x32_bf16 v[114:117], v[186:189], v[194:197], v[114:117]
	v_mfma_f32_16x16x32_bf16 v[102:105], v[178:181], v[202:205], v[102:105]
	v_mfma_f32_16x16x32_bf16 v[98:101], v[186:189], v[202:205], v[98:101]
	v_mfma_f32_16x16x32_bf16 v[84:87], v[178:181], v[210:213], v[84:87]
	v_mfma_f32_16x16x32_bf16 v[80:83], v[186:189], v[210:213], v[80:83]
	v_mfma_f32_16x16x32_bf16 v[68:71], v[178:181], v[218:221], v[68:71]
	v_mfma_f32_16x16x32_bf16 v[64:67], v[186:189], v[218:221], v[64:67]
	s_setprio 0
	s_barrier
	s_add_i32 s50, s50, s8
	s_mov_b32 m0, s50
	ds_read_b128 v[190:193], v149 offset:49152
	ds_read_b128 v[194:197], v149 offset:50176
	ds_read_b128 v[198:201], v149 offset:51200
	ds_read_b128 v[202:205], v149 offset:52224
	ds_read_b128 v[206:209], v149 offset:53248
	ds_read_b128 v[210:213], v149 offset:54272
	ds_read_b128 v[214:217], v149 offset:55296
	ds_read_b128 v[218:221], v149 offset:56320
	global_load_lds_dwordx4 v96, s[100:101]
	s_add_i32 m0, s50, 0x2000
	s_add_i32 s50, s54, s8
	global_load_lds_dwordx4 v134, s[100:101]
	s_mov_b32 m0, s50
	s_nop 0
	s_add_u32 s100, s100, s34
	s_addc_u32 s101, s101, s35
	global_load_lds_dwordx4 v96, s[100:101]
	s_add_i32 m0, s50, 0x2000
	s_nop 0
	global_load_lds_dwordx4 v134, s[100:101]
	s_mov_b32 m0, s77
	s_nop 0
	s_add_u32 s100, s78, s12
	s_addc_u32 s101, s79, s13
	global_load_lds_dwordx4 v130, s[100:101]
	s_mov_b32 m0, s86
	s_nop 0
	global_load_lds_dwordx4 v132, s[100:101]
	s_waitcnt vmcnt(8)
	s_waitcnt lgkmcnt(0)
	s_barrier
	s_setprio 1
	s_waitcnt lgkmcnt(0)
	v_mfma_f32_16x16x32_bf16 v[60:63], v[140:143], v[190:193], v[60:63]
	v_mfma_f32_16x16x32_bf16 v[56:59], v[166:169], v[190:193], v[56:59]
	v_mfma_f32_16x16x32_bf16 v[44:47], v[140:143], v[198:201], v[44:47]
	v_mfma_f32_16x16x32_bf16 v[40:43], v[166:169], v[198:201], v[40:43]
	v_mfma_f32_16x16x32_bf16 v[28:31], v[140:143], v[206:209], v[28:31]
	v_mfma_f32_16x16x32_bf16 v[24:27], v[166:169], v[206:209], v[24:27]
	v_mfma_f32_16x16x32_bf16 v[12:15], v[140:143], v[214:217], v[12:15]
	v_mfma_f32_16x16x32_bf16 v[8:11], v[166:169], v[214:217], v[8:11]
	v_mfma_f32_16x16x32_bf16 v[60:63], v[162:165], v[194:197], v[60:63]
	v_mfma_f32_16x16x32_bf16 v[56:59], v[170:173], v[194:197], v[56:59]
	v_mfma_f32_16x16x32_bf16 v[44:47], v[162:165], v[202:205], v[44:47]
	v_mfma_f32_16x16x32_bf16 v[40:43], v[170:173], v[202:205], v[40:43]
	v_mfma_f32_16x16x32_bf16 v[28:31], v[162:165], v[210:213], v[28:31]
	v_mfma_f32_16x16x32_bf16 v[24:27], v[170:173], v[210:213], v[24:27]
	v_mfma_f32_16x16x32_bf16 v[12:15], v[162:165], v[218:221], v[12:15]
	v_mfma_f32_16x16x32_bf16 v[8:11], v[170:173], v[218:221], v[8:11]
	s_setprio 0
	s_setprio 1
	v_mfma_f32_16x16x32_bf16 v[52:55], v[174:177], v[190:193], v[52:55]
	v_mfma_f32_16x16x32_bf16 v[48:51], v[182:185], v[190:193], v[48:51]
	v_mfma_f32_16x16x32_bf16 v[36:39], v[174:177], v[198:201], v[36:39]
	v_mfma_f32_16x16x32_bf16 v[32:35], v[182:185], v[198:201], v[32:35]
	v_mfma_f32_16x16x32_bf16 v[20:23], v[174:177], v[206:209], v[20:23]
	v_mfma_f32_16x16x32_bf16 v[16:19], v[182:185], v[206:209], v[16:19]
	v_mfma_f32_16x16x32_bf16 v[4:7], v[174:177], v[214:217], v[4:7]
	v_mfma_f32_16x16x32_bf16 v[0:3], v[182:185], v[214:217], v[0:3]
	v_mfma_f32_16x16x32_bf16 v[52:55], v[178:181], v[194:197], v[52:55]
	v_mfma_f32_16x16x32_bf16 v[48:51], v[186:189], v[194:197], v[48:51]
	v_mfma_f32_16x16x32_bf16 v[36:39], v[178:181], v[202:205], v[36:39]
	v_mfma_f32_16x16x32_bf16 v[32:35], v[186:189], v[202:205], v[32:35]
	v_mfma_f32_16x16x32_bf16 v[20:23], v[178:181], v[210:213], v[20:23]
	v_mfma_f32_16x16x32_bf16 v[16:19], v[186:189], v[210:213], v[16:19]
	v_mfma_f32_16x16x32_bf16 v[4:7], v[178:181], v[218:221], v[4:7]
	v_mfma_f32_16x16x32_bf16 v[0:3], v[186:189], v[218:221], v[0:3]
	s_setprio 0
	s_barrier
	s_add_u32 s42, s42, 0x100
	s_addc_u32 s43, s43, 0
	s_add_u32 s48, s48, 0x100
	s_addc_u32 s49, s49, 0
	s_cmp_ge_u32 s51, s64
	s_mov_b32 s50, s51
	s_cbranch_scc0 .LBB0_333
	s_branch .Lk_done
